# also normmod1(l=0)->inproj barrier replaced by H-panel counters (H rows written through)
# baseline (speedup 1.0000x reference)
.LBB0_8:
	v_writelane_b32 v254, s78, 24
	s_mov_b32 s0, s49
	s_ashr_i32 s1, s0, 31
	v_writelane_b32 v254, s79, 25
	v_writelane_b32 v254, s76, 26
	v_readlane_b32 s2, v253, 3
	v_readlane_b32 s3, v253, 4
	v_writelane_b32 v254, s77, 27
	v_writelane_b32 v254, s74, 28
	s_add_u32 s0, s2, s0
	s_addc_u32 s1, s3, s1
	v_writelane_b32 v254, s75, 29
	v_writelane_b32 v254, s66, 30
	v_readlane_b32 s24, v253, 62
	v_writelane_b32 v254, s67, 31
	v_readlane_b32 s25, v253, 63
	s_load_dwordx16 s[52:67], s[0:1], 0x0
	s_load_dwordx2 s[30:31], s[0:1], 0x70
	s_load_dwordx4 s[36:39], s[0:1], 0x60
	s_load_dwordx8 s[12:19], s[0:1], 0x40
	s_load_dwordx2 s[2:3], s[0:1], 0x88
	s_load_dwordx8 s[68:75], s[0:1], 0x98
	s_load_dwordx16 s[80:95], s[0:1], 0xc0
	s_load_dwordx4 s[96:99], s[0:1], 0x120
	s_load_dwordx8 s[4:11], s[0:1], 0x100
	s_waitcnt lgkmcnt(0)
	s_movk_i32 s100, 0
	s_cmp_eq_u32 s46, 6
	s_cselect_b32 s100, 8, s100
	s_cmp_eq_u32 s46, 10
	s_cselect_b32 s100, 16, s100
	s_cmp_eq_u32 s46, 15
	s_cselect_b32 s100, 24, s100
	s_cmp_eq_u32 s46, 19
	s_cselect_b32 s100, 32, s100
	s_cmp_eq_u32 s46, 2
	s_cselect_b32 s100, 16, s100
	s_cmp_eq_u32 s100, 0
	s_cbranch_scc1 .Lpf_done
	v_lshrrev_b32_e32 v2, 6, v1
	s_nop 1
	v_readfirstlane_b32 s0, v2
	s_cmp_lg_u32 s0, 0
	s_cbranch_scc1 .Lpf_wait
	v_readlane_b32 s0, v253, 0
	s_lshr_b32 s1, s0, 4
	s_mov_b32 vcc_lo, 15
	s_mov_b32 vcc_hi, 0
	s_cmp_eq_u32 s46, 19
	s_cbranch_scc0 .Lpf_t1
	s_lshr_b32 s1, s0, 5
	s_mov_b32 vcc_lo, 7
.Lpf_t1:
	s_cmp_eq_u32 s46, 2
	s_cbranch_scc0 .Lpf_t2
.Lpf_tc:
	s_and_b32 s1, s0, 7
	s_lshl_b32 s1, s1, 2
	s_bfe_u32 s0, s0, 0x20003
	s_or_b32 s1, s1, s0
	s_mov_b32 vcc_lo, 31
	s_movk_i32 vcc_hi, 0x80
.Lpf_t2:
	v_lshl_add_u32 v4, v194, 2, vcc_hi
	v_and_b32_e32 v2, vcc_lo, v194
	v_cmp_eq_u32_e32 vcc, s1, v2
	v_mov_b32_e32 v3, s100
	v_cndmask_b32_e32 v3, 0, v3, vcc
	v_cmp_gt_u32_e32 vcc, 32, v194
	v_cndmask_b32_e32 v3, 0, v3, vcc
	v_readlane_b32 s0, v253, 5
	v_readlane_b32 s1, v253, 6
	s_movk_i32 s100, 0x1000
	s_nop 4
.Lpf_poll:
	global_load_dword v2, v4, s[0:1] sc1
	s_waitcnt vmcnt(0)
	v_cmp_lt_u32_e32 vcc, v2, v3
	s_cbranch_vccz .Lpf_ok
	s_sleep 1
	s_add_i32 s100, s100, -1
	s_cmp_lg_u32 s100, 0
	s_cbranch_scc1 .Lpf_poll

.LBB0_642:
	s_or_b64 exec, exec, s[8:9]
	s_waitcnt vmcnt(0)
	v_mov_b32_e32 v42, v15
	v_mov_b32_e32 v43, v11
	v_cmp_lt_i32_e32 vcc, v196, v195
	v_mov_b32_e32 v40, v14
	v_mov_b32_e32 v41, v10
	v_pk_mul_f32 v[42:43], v[42:43], v[42:43]
	v_cndmask_b32_e32 v39, v194, v196, vcc
	v_pk_fma_f32 v[40:41], v[40:41], v[40:41], v[42:43]
	v_mov_b32_e32 v42, v16
	v_mov_b32_e32 v43, v12
	v_lshlrev_b32_e32 v66, 2, v39
	v_pk_fma_f32 v[40:41], v[42:43], v[42:43], v[40:41]
	v_mov_b32_e32 v42, v17
	v_mov_b32_e32 v43, v13
	v_lshrrev_b32_e32 v39, 10, v44
	v_readlane_b32 s68, v254, 60
	v_pk_fma_f32 v[58:59], v[42:43], v[42:43], v[40:41]
	v_mov_b32_e32 v42, v7
	v_mov_b32_e32 v43, v3
	v_add_u32_e32 v39, 1, v39
	v_readlane_b32 s72, v252, 0
	v_readlane_b32 s73, v252, 1
	v_mov_b32_e32 v40, v6
	v_mov_b32_e32 v41, v2
	v_pk_mul_f32 v[42:43], v[42:43], v[42:43]
	v_cndmask_b32_e64 v39, v39, 0, s[40:41]
	v_readlane_b32 s74, v252, 2
	v_readlane_b32 s75, v252, 3
	s_mov_b64 s[16:17], s[72:73]
	v_pk_fma_f32 v[54:55], v[40:41], v[40:41], v[42:43]
	v_add_u32_e32 v39, s10, v39
	v_mov_b64_e32 v[40:41], s[16:17]
	v_mad_i64_i32 v[40:41], s[8:9], v39, s29, v[40:41]
	s_mov_b64 s[8:9], 0x1000
	s_nop 0
	v_lshl_add_u64 v[42:43], v[40:41], 0, s[8:9]
	v_mov_b32_e32 v39, v163
	v_mov_b32_e32 v56, v8
	v_lshl_add_u64 v[40:41], v[40:41], 0, v[38:39]
	v_lshl_add_u64 v[44:45], v[42:43], 0, v[38:39]
	v_mov_b32_e32 v57, v4
	global_load_dwordx4 v[46:49], v[40:41], off
	global_load_dwordx4 v[50:53], v[44:45], off
	v_pk_fma_f32 v[44:45], v[56:57], v[56:57], v[54:55]
	v_mov_b32_e32 v54, v9
	v_mov_b32_e32 v55, v5
	v_mov_b32_e32 v56, v31
	v_mov_b32_e32 v57, v27
	v_pk_fma_f32 v[44:45], v[54:55], v[54:55], v[44:45]
	v_mov_b32_e32 v54, v30
	v_mov_b32_e32 v55, v26
	v_pk_mul_f32 v[56:57], v[56:57], v[56:57]
	v_mov_b32_e32 v62, v32
	v_pk_fma_f32 v[60:61], v[54:55], v[54:55], v[56:57]
	global_load_dwordx4 v[54:57], v38, s[0:1]
	v_mov_b32_e32 v63, v28
	v_pk_fma_f32 v[60:61], v[62:63], v[62:63], v[60:61]
	v_mov_b32_e32 v62, v33
	v_mov_b32_e32 v63, v29
	v_mov_b32_e32 v64, v23
	v_mov_b32_e32 v65, v19
	v_pk_fma_f32 v[60:61], v[62:63], v[62:63], v[60:61]
	v_mov_b32_e32 v62, v22
	v_mov_b32_e32 v63, v18
	v_pk_mul_f32 v[64:65], v[64:65], v[64:65]
	v_cmp_lt_i32_e32 vcc, v197, v195
	v_pk_fma_f32 v[62:63], v[62:63], v[62:63], v[64:65]
	v_mov_b32_e32 v64, v24
	v_mov_b32_e32 v65, v20
	v_pk_fma_f32 v[62:63], v[64:65], v[64:65], v[62:63]
	v_mov_b32_e32 v64, v25
	v_mov_b32_e32 v65, v21
	v_pk_fma_f32 v[62:63], v[64:65], v[64:65], v[62:63]
	v_mov_b32_e32 v64, v60
	v_mov_b32_e32 v65, v58
	v_mov_b32_e32 v58, v61
	v_pk_add_f32 v[58:59], v[64:65], v[58:59]
	v_mov_b32_e32 v60, v62
	v_mov_b32_e32 v61, v44
	v_pk_add_f32 v[58:59], v[58:59], v[60:61]
	v_mov_b32_e32 v44, v63
	v_pk_add_f32 v[44:45], v[58:59], v[44:45]
	ds_bpermute_b32 v59, v66, v45
	ds_bpermute_b32 v58, v66, v44
	v_cndmask_b32_e32 v39, v194, v197, vcc
	v_lshlrev_b32_e32 v39, 2, v39
	v_cmp_lt_i32_e32 vcc, v198, v195
	s_mov_b32 s8, 0x3a800000
	s_waitcnt lgkmcnt(0)
	v_pk_add_f32 v[44:45], v[44:45], v[58:59]
	ds_bpermute_b32 v59, v39, v45
	ds_bpermute_b32 v58, v39, v44
	v_cndmask_b32_e32 v39, v194, v198, vcc
	v_lshlrev_b32_e32 v39, 2, v39
	v_cmp_lt_i32_e32 vcc, v199, v195
	v_readlane_b32 s69, v254, 61
	s_waitcnt lgkmcnt(0)
	v_pk_add_f32 v[44:45], v[44:45], v[58:59]
	ds_bpermute_b32 v59, v39, v45
	ds_bpermute_b32 v58, v39, v44
	v_cndmask_b32_e32 v39, v194, v199, vcc
	v_lshlrev_b32_e32 v39, 2, v39
	v_cmp_lt_i32_e32 vcc, v200, v195
	v_readlane_b32 s70, v254, 62
	s_waitcnt lgkmcnt(0)
	v_pk_add_f32 v[44:45], v[44:45], v[58:59]
	ds_bpermute_b32 v59, v39, v45
	ds_bpermute_b32 v58, v39, v44
	v_cndmask_b32_e32 v39, v194, v200, vcc
	v_lshlrev_b32_e32 v39, 2, v39
	v_cmp_lt_i32_e32 vcc, v201, v195
	v_readlane_b32 s71, v254, 63
	s_waitcnt lgkmcnt(0)
	v_pk_add_f32 v[44:45], v[44:45], v[58:59]
	ds_bpermute_b32 v59, v39, v45
	ds_bpermute_b32 v58, v39, v44
	v_cndmask_b32_e32 v39, v194, v201, vcc
	v_lshlrev_b32_e32 v39, 2, v39
	s_mov_b64 s[18:19], s[74:75]
	v_readlane_b32 s68, v254, 44
	s_waitcnt lgkmcnt(0)
	v_pk_add_f32 v[44:45], v[44:45], v[58:59]
	ds_bpermute_b32 v59, v39, v45
	ds_bpermute_b32 v58, v39, v44
	v_readlane_b32 s82, v254, 58
	v_readlane_b32 s83, v254, 59
	v_readlane_b32 s14, v254, 22
	s_waitcnt vmcnt(1)
	v_pk_add_f32 v[50:51], v[50:51], 1.0 op_sel_hi:[1,0]
	s_waitcnt lgkmcnt(0)
	v_pk_add_f32 v[44:45], v[44:45], v[58:59]
	v_pk_add_f32 v[52:53], v[52:53], 1.0 op_sel_hi:[1,0]
	v_pk_fma_f32 v[58:59], v[44:45], s[8:9], v[164:165] op_sel_hi:[1,0,0]
	s_mov_b32 s8, 0x800000
	v_mul_f32_e32 v39, 0x4b800000, v59
	v_cmp_gt_f32_e32 vcc, s8, v59
	v_lshl_add_u64 v[44:45], s[82:83], 0, v[36:37]
	v_lshl_add_u64 v[44:45], v[44:45], 0, v[162:163]
	v_cndmask_b32_e32 v39, v59, v39, vcc
	v_rsq_f32_e32 v39, v39
	v_or_b32_e32 v162, 0x400, v38
	v_readlane_b32 s15, v254, 23
	s_add_u32 s82, s82, s14
	v_mul_f32_e32 v59, 0x45800000, v39
	v_cndmask_b32_e32 v60, v39, v59, vcc
	v_mul_f32_e32 v39, 0x4b800000, v58
	v_cmp_gt_f32_e32 vcc, s8, v58
	v_pk_mul_f32 v[14:15], v[14:15], v[60:61] op_sel_hi:[1,0]
	v_pk_mul_f32 v[16:17], v[16:17], v[60:61] op_sel_hi:[1,0]
	v_cndmask_b32_e32 v39, v58, v39, vcc
	v_rsq_f32_e32 v39, v39
	s_waitcnt vmcnt(0)
	v_pk_mul_f32 v[14:15], v[54:55], v[14:15]
	v_pk_mul_f32 v[16:17], v[56:57], v[16:17]
	v_pk_fma_f32 v[14:15], v[14:15], v[50:51], v[46:47]
	v_pk_fma_f32 v[16:17], v[16:17], v[52:53], v[48:49]
	v_cvt_pk_bf16_f32 v14, v14, v15
	v_cvt_pk_bf16_f32 v15, v16, v17
	global_store_dwordx2 v[44:45], v[14:15], off sc1
	v_mul_f32_e32 v14, 0x45800000, v39
	v_cndmask_b32_e32 v58, v39, v14, vcc
	v_pk_mul_f32 v[14:15], v[30:31], v[58:59] op_sel_hi:[1,0]
	v_pk_mul_f32 v[16:17], v[32:33], v[58:59] op_sel_hi:[1,0]
	v_pk_mul_f32 v[14:15], v[54:55], v[14:15]
	v_pk_mul_f32 v[16:17], v[56:57], v[16:17]
	v_pk_fma_f32 v[14:15], v[50:51], v[14:15], v[46:47]
	v_pk_fma_f32 v[16:17], v[52:53], v[16:17], v[48:49]
	v_cvt_pk_bf16_f32 v14, v14, v15
	v_cvt_pk_bf16_f32 v15, v16, v17
	global_store_dwordx2 v[44:45], v[14:15], off offset:2048 sc1
	global_load_dwordx4 v[14:17], v38, s[0:1] offset:1024
	v_lshl_add_u64 v[30:31], v[42:43], 0, v[162:163]
	global_load_dwordx4 v[30:33], v[30:31], off
	s_nop 0
	global_load_dwordx4 v[46:49], v[40:41], off offset:1024
	v_pk_mul_f32 v[10:11], v[10:11], v[60:61] op_sel_hi:[1,0]
	v_pk_mul_f32 v[12:13], v[12:13], v[60:61] op_sel_hi:[1,0]
	v_pk_mul_f32 v[26:27], v[26:27], v[58:59] op_sel_hi:[1,0]
	v_pk_mul_f32 v[28:29], v[28:29], v[58:59] op_sel_hi:[1,0]
	v_or_b32_e32 v162, 0x800, v38
	v_lshl_add_u64 v[50:51], v[42:43], 0, v[162:163]
	v_pk_mul_f32 v[6:7], v[6:7], v[60:61] op_sel_hi:[1,0]
	v_pk_mul_f32 v[8:9], v[8:9], v[60:61] op_sel_hi:[1,0]
	v_pk_mul_f32 v[22:23], v[22:23], v[58:59] op_sel_hi:[1,0]
	v_pk_mul_f32 v[24:25], v[24:25], v[58:59] op_sel_hi:[1,0]
	v_or_b32_e32 v162, 0xc00, v38
	v_readlane_b32 s69, v254, 45
	v_readlane_b32 s70, v254, 46
	v_readlane_b32 s71, v254, 47
	v_readlane_b32 s72, v254, 48
	v_readlane_b32 s73, v254, 49
	v_readlane_b32 s74, v254, 50
	v_readlane_b32 s75, v254, 51
	v_readlane_b32 s76, v254, 52
	v_readlane_b32 s77, v254, 53
	v_readlane_b32 s78, v254, 54
	v_readlane_b32 s79, v254, 55
	v_readlane_b32 s80, v254, 56
	v_readlane_b32 s81, v254, 57
	s_addc_u32 s83, s83, s15
	v_writelane_b32 v254, s68, 44
	s_add_u32 s18, s18, s14
	s_addc_u32 s19, s19, s15
	v_writelane_b32 v254, s69, 45
	v_writelane_b32 v254, s70, 46
	v_writelane_b32 v254, s71, 47
	v_writelane_b32 v254, s72, 48
	v_writelane_b32 v254, s73, 49
	v_writelane_b32 v254, s74, 50
	v_writelane_b32 v254, s75, 51
	v_writelane_b32 v254, s76, 52
	v_writelane_b32 v254, s77, 53
	v_writelane_b32 v254, s78, 54
	v_writelane_b32 v254, s79, 55
	v_writelane_b32 v254, s80, 56
	v_writelane_b32 v254, s81, 57
	v_writelane_b32 v254, s82, 58
	v_writelane_b32 v254, s83, 59
	v_writelane_b32 v254, s12, 60
	v_pk_mul_f32 v[2:3], v[2:3], v[60:61] op_sel_hi:[1,0]
	v_pk_mul_f32 v[4:5], v[4:5], v[60:61] op_sel_hi:[1,0]
	v_lshl_add_u64 v[34:35], v[34:35], 0, s[84:85]
	s_movk_i32 s8, 0x1fff
	v_writelane_b32 v254, s13, 61
	v_writelane_b32 v252, s16, 0
	v_pk_mul_f32 v[18:19], v[18:19], v[58:59] op_sel_hi:[1,0]
	v_pk_mul_f32 v[20:21], v[20:21], v[58:59] op_sel_hi:[1,0]
	v_cmp_lt_i32_e32 vcc, s8, v34
	v_writelane_b32 v254, s14, 62
	v_writelane_b32 v252, s17, 1
	v_writelane_b32 v254, s15, 63
	v_writelane_b32 v252, s18, 2
	s_or_b64 s[6:7], vcc, s[6:7]
	v_writelane_b32 v252, s19, 3
	s_waitcnt vmcnt(2)
	v_pk_mul_f32 v[10:11], v[10:11], v[14:15]
	s_waitcnt vmcnt(1)
	v_pk_add_f32 v[30:31], v[30:31], 1.0 op_sel_hi:[1,0]
	v_pk_mul_f32 v[12:13], v[12:13], v[16:17]
	v_pk_add_f32 v[32:33], v[32:33], 1.0 op_sel_hi:[1,0]
	v_pk_mul_f32 v[14:15], v[14:15], v[26:27]
	v_pk_mul_f32 v[16:17], v[16:17], v[28:29]
	s_waitcnt vmcnt(0)
	v_pk_fma_f32 v[10:11], v[10:11], v[30:31], v[46:47]
	v_pk_fma_f32 v[12:13], v[12:13], v[32:33], v[48:49]
	v_pk_fma_f32 v[14:15], v[30:31], v[14:15], v[46:47]
	v_pk_fma_f32 v[16:17], v[32:33], v[16:17], v[48:49]
	v_cvt_pk_bf16_f32 v10, v10, v11
	v_cvt_pk_bf16_f32 v11, v12, v13
	v_cvt_pk_bf16_f32 v12, v14, v15
	v_cvt_pk_bf16_f32 v13, v16, v17
	global_store_dwordx2 v[44:45], v[10:11], off offset:512 sc1
	global_store_dwordx2 v[44:45], v[12:13], off offset:2560 sc1
	global_load_dwordx4 v[10:13], v38, s[0:1] offset:2048
	s_nop 0
	global_load_dwordx4 v[14:17], v[50:51], off
	global_load_dwordx4 v[26:29], v[40:41], off offset:2048
	v_lshl_add_u64 v[30:31], v[42:43], 0, v[162:163]
	s_waitcnt vmcnt(2)
	v_pk_mul_f32 v[6:7], v[6:7], v[10:11]
	s_waitcnt vmcnt(1)
	v_pk_add_f32 v[14:15], v[14:15], 1.0 op_sel_hi:[1,0]
	v_pk_mul_f32 v[8:9], v[8:9], v[12:13]
	v_pk_add_f32 v[16:17], v[16:17], 1.0 op_sel_hi:[1,0]
	v_pk_mul_f32 v[10:11], v[22:23], v[10:11]
	v_pk_mul_f32 v[12:13], v[24:25], v[12:13]
	s_waitcnt vmcnt(0)
	v_pk_fma_f32 v[6:7], v[6:7], v[14:15], v[26:27]
	v_pk_fma_f32 v[8:9], v[8:9], v[16:17], v[28:29]
	v_pk_fma_f32 v[10:11], v[10:11], v[14:15], v[26:27]
	v_pk_fma_f32 v[12:13], v[12:13], v[16:17], v[28:29]
	v_cvt_pk_bf16_f32 v6, v6, v7
	v_cvt_pk_bf16_f32 v7, v8, v9
	v_cvt_pk_bf16_f32 v8, v10, v11
	v_cvt_pk_bf16_f32 v9, v12, v13
	global_store_dwordx2 v[44:45], v[6:7], off offset:1024 sc1
	global_store_dwordx2 v[44:45], v[8:9], off offset:3072 sc1
	global_load_dwordx4 v[6:9], v38, s[0:1] offset:3072
	s_nop 0
	global_load_dwordx4 v[10:13], v[30:31], off
	global_load_dwordx4 v[14:17], v[40:41], off offset:3072
	s_waitcnt vmcnt(2)
	v_pk_mul_f32 v[2:3], v[2:3], v[6:7]
	s_waitcnt vmcnt(1)
	v_pk_add_f32 v[10:11], v[10:11], 1.0 op_sel_hi:[1,0]
	v_pk_mul_f32 v[4:5], v[4:5], v[8:9]
	v_pk_add_f32 v[12:13], v[12:13], 1.0 op_sel_hi:[1,0]
	v_pk_mul_f32 v[6:7], v[18:19], v[6:7]
	v_pk_mul_f32 v[8:9], v[20:21], v[8:9]
	s_waitcnt vmcnt(0)
	v_pk_fma_f32 v[2:3], v[2:3], v[10:11], v[14:15]
	v_pk_fma_f32 v[4:5], v[4:5], v[12:13], v[16:17]
	v_pk_fma_f32 v[6:7], v[6:7], v[10:11], v[14:15]
	v_pk_fma_f32 v[8:9], v[8:9], v[12:13], v[16:17]
	v_cvt_pk_bf16_f32 v2, v2, v3
	v_cvt_pk_bf16_f32 v3, v4, v5
	v_cvt_pk_bf16_f32 v4, v6, v7
	v_cvt_pk_bf16_f32 v5, v8, v9
	global_store_dwordx2 v[44:45], v[2:3], off offset:1536 sc1
	global_store_dwordx2 v[44:45], v[4:5], off offset:3584 sc1
	s_andn2_b64 exec, exec, s[6:7]
	s_cbranch_execz .LBB0_675

.LBB0_675:
	s_or_b64 exec, exec, s[2:3]
	s_waitcnt vmcnt(0)
	s_barrier
	v_lshrrev_b32_e32 v2, 6, v1
	s_nop 1
	v_readfirstlane_b32 s6, v2
	s_cmp_lg_u32 s6, 0
	s_cbranch_scc1 .Lpf_rel1
	v_readlane_b32 s68, v253, 5
	v_readlane_b32 s69, v253, 6
	v_readlane_b32 s6, v253, 0
	s_lshr_b32 s6, s6, 4
	s_lshl_b32 s6, s6, 2
	s_add_u32 s6, s6, 0x80
	v_lshlrev_b32_e32 v2, 6, v194
	v_add_u32_e32 v2, s6, v2
	v_mov_b32_e32 v3, 1
	s_nop 3
	s_mov_b64 exec, 3
	global_atomic_add v2, v3, s[68:69]
	s_mov_b64 exec, -1
.Lpf_rel1:
	s_add_i32 s0, s46, -10
	s_cmp_lt_u32 s0, 9
	s_cselect_b64 s[0:1], -1, 0
	s_cmpk_lt_i32 s13, 0x200
	s_cselect_b64 s[2:3], -1, 0
	s_and_b64 s[0:1], s[0:1], s[2:3]
	s_and_b64 vcc, exec, s[0:1]
	s_cbranch_vccz .LBB0_693
	v_readlane_b32 s76, v254, 36
	v_readlane_b32 s78, v254, 38
	v_readlane_b32 s79, v254, 39
	s_add_i32 s10, s13, 0x140
	s_mov_b64 s[2:3], s[78:79]
	s_add_u32 s11, s2, 0x1a00000
	s_mov_b64 s[52:53], s[46:47]
	s_addc_u32 s12, s3, 0
	s_lshl_b32 s0, s13, 9
	v_readlane_b32 s44, v254, 32
	s_add_i32 s13, s0, 0x28000
	s_mov_b32 s18, 0xa02000
	s_mov_b32 s19, 0xa04000
	s_mov_b32 s30, 0xa06000
	s_mov_b32 s31, 0xa08000
	s_mov_b32 s38, 0xa0a000
	s_mov_b32 s39, 0xa0c000
	s_mov_b32 s40, 0xa0e000
	s_mov_b32 s41, 0xa0f000
	v_readlane_b32 s45, v254, 33
	v_readlane_b32 s46, v254, 34
	v_readlane_b32 s47, v254, 35
	s_movk_i32 s42, 0x1ff
	v_readlane_b32 s77, v254, 37
	v_readlane_b32 s80, v254, 40
	v_readlane_b32 s81, v254, 41
	v_readlane_b32 s82, v254, 42
	v_readlane_b32 s83, v254, 43
	s_branch .LBB0_678

.LBB0_727:
	s_mov_b64 s[2:3], s[46:47]
	s_add_i32 s18, s2, 1
	s_cmp_ge_i32 s18, s3
	v_readlane_b32 s30, v254, 6
	v_readlane_b32 s38, v254, 8
	v_readlane_b32 s56, v254, 22
	v_readlane_b32 s31, v254, 7
	v_readlane_b32 s39, v254, 9
	v_readlane_b32 s57, v254, 23
	s_cbranch_scc1 .LBB0_781
	s_cmp_eq_u32 s2, 5
	s_cbranch_scc1 .LBB0_781
	s_cmp_eq_u32 s2, 14
	s_cbranch_scc1 .LBB0_781
	s_cmp_eq_u32 s2, 9
	s_cbranch_scc1 .LBB0_781
	s_cmp_eq_u32 s2, 18
	s_cbranch_scc1 .LBB0_781
	s_cmp_eq_u32 s2, 4
	s_cbranch_scc1 .LBB0_781
	s_cmp_eq_u32 s2, 13
	s_cbranch_scc1 .LBB0_781
	s_cmp_eq_u32 s2, 1
	s_cbranch_scc1 .LBB0_781
	s_waitcnt vmcnt(0)
	s_waitcnt lgkmcnt(0)
	s_barrier
	s_mov_b64 s[2:3], exec
	v_readlane_b32 s4, v253, 7
	v_readlane_b32 s5, v253, 8
	s_and_b64 s[4:5], s[2:3], s[4:5]
	s_mov_b64 exec, s[4:5]
	s_cbranch_execz .LBB0_780
	s_add_i32 s13, 0, 0x24000
	s_mov_b64 s[4:5], src_shared_base
	s_cmp_lg_u32 s13, -1
	s_cselect_b32 s4, s13, 0
	s_cselect_b32 s6, s5, 0
	s_add_i32 s12, 0, 0x24004
	s_cmp_lg_u32 s12, -1
	v_mov_b32_e32 v2, s4
	v_mov_b32_e32 v3, s6
	s_cselect_b32 s4, s12, 0
	s_cselect_b32 s5, s5, 0
	s_waitcnt vmcnt(0) expcnt(0) lgkmcnt(0)
	s_and_b32 s4, s101, 0xffff
	v_mov_b32_e32 v4, s4
	v_mov_b32_e32 v2, s4
	v_mov_b32_e32 v3, s5
	s_lshr_b32 s4, s101, 16
	v_mov_b32_e32 v2, s4
	s_waitcnt vmcnt(0) lgkmcnt(0)
	v_cmp_eq_u32_e32 vcc, 0, v4
	s_and_saveexec_b64 s[4:5], vcc
	s_cbranch_execz .LBB0_744
	s_mov_b32 s14, 1
	s_branch .LBB0_732
